# wout_v89 + phase-5 main tile loop uses the 3-stage software-pipelined K loop of phase 1
# baseline (speedup 1.0000x reference)
.LBB0_1151:
	s_add_u32 s8, s20, 0x10a40000
	s_addc_u32 s9, s21, 0
	s_add_u32 s6, s20, 0x11048000
	s_addc_u32 s7, s21, 0
	s_abs_i32 s0, s29
	v_cvt_f32_u32_e32 v0, s0
	s_sub_i32 s1, s29, s28
	s_add_i32 s4, s1, 0x7f
	s_sub_i32 s1, 0xffffff81, s1
	v_rcp_iflag_f32_e32 v0, v0
	s_xor_b32 s5, s4, s29
	s_max_i32 s1, s4, s1
	s_sub_i32 s4, 0, s0
	v_mul_f32_e32 v0, 0x4f7ffffe, v0
	v_cvt_u32_f32_e32 v0, v0
	s_ashr_i32 s5, s5, 31
	s_waitcnt vmcnt(16)
	v_bfe_u32 v140, v138, 6, 1
	v_bfe_u32 v139, v138, 4, 2
	v_readfirstlane_b32 s10, v0
	s_mul_i32 s4, s4, s10
	s_mul_hi_u32 s4, s10, s4
	s_add_i32 s10, s10, s4
	s_mul_hi_u32 s4, s1, s10
	s_mul_i32 s10, s4, s0
	s_sub_i32 s1, s1, s10
	s_add_i32 s10, s4, 1
	s_sub_i32 s11, s1, s0
	s_cmp_ge_u32 s1, s0
	s_cselect_b32 s4, s10, s4
	s_cselect_b32 s1, s11, s1
	s_add_i32 s10, s4, 1
	s_cmp_ge_u32 s1, s0
	s_cselect_b32 s0, s10, s4
	s_xor_b32 s0, s0, s5
	s_sub_i32 s0, s0, s5
	s_lshl_b32 s56, s0, 3
	s_cmp_ge_i32 s88, s56
	s_mov_b32 s11, 0
	s_cbranch_scc1 .LBB0_1164
	v_lshlrev_b32_e32 v1, 3, v139
	v_and_b32_e32 v0, 15, v138
	v_lshl_or_b32 v1, v140, 7, v1
	s_movk_i32 s4, 0x110
	v_add_u32_e32 v3, 0x100, v138
	v_add_u32_e32 v4, 0x200, v138
	v_add_u32_e32 v5, 0x300, v138
	v_add_u32_e32 v6, 0x400, v138
	v_add_u32_e32 v7, 0x500, v138
	v_add_u32_e32 v8, 0x600, v138
	v_add_u32_e32 v9, 0x700, v138
	v_lshlrev_b32_e32 v2, 4, v138
	v_ashrrev_i32_e32 v141, 4, v138
	v_mad_u32_u24 v142, v0, s4, v1
	v_or_b32_e32 v0, 0x70, v138
	v_ashrrev_i32_e32 v143, 4, v3
	v_ashrrev_i32_e32 v144, 4, v4
	v_ashrrev_i32_e32 v145, 4, v5
	v_ashrrev_i32_e32 v146, 4, v6
	v_ashrrev_i32_e32 v147, 4, v7
	v_ashrrev_i32_e32 v148, 4, v8
	v_ashrrev_i32_e32 v149, 4, v9
	v_and_b32_e32 v128, 0xf0, v2
	v_mov_b32_e32 v129, 0
	v_mul_lo_u32 v2, v141, s4
	s_movk_i32 s5, 0x80
	v_mul_lo_u32 v0, v0, s4
	v_mul_lo_u32 v3, v143, s4
	v_mul_lo_u32 v4, v144, s4
	v_mul_lo_u32 v5, v145, s4
	v_mul_lo_u32 v6, v146, s4
	v_mul_lo_u32 v7, v147, s4
	v_mul_lo_u32 v8, v148, s4
	v_mul_lo_u32 v9, v149, s4
	v_and_b32_e32 v10, 0xffffff80, v138
	v_lshl_add_u64 v[130:131], s[6:7], 0, v[128:129]
	v_cmp_gt_u32_e64 s[0:1], s5, v138
	v_cmp_eq_u32_e64 s[4:5], s5, v10
	s_lshl_b32 s57, s88, 7
	s_lshl_b32 s58, s89, 7
	s_mov_b64 s[46:47], 0
	s_mov_b64 s[12:13], 0x4000
	s_mov_b64 s[14:15], 0x8000
	s_mov_b64 s[16:17], 0xc000
	s_mov_b64 s[30:31], 0x1000
	s_mov_b64 s[34:35], 0x14000
	s_mov_b64 s[36:37], 0x18000
	s_mov_b64 s[38:39], 0x1c000
	s_mov_b64 s[100:101], 0x10000
	v_and_b32_e32 v254, 0x7f, v138
	v_lshlrev_b32_e32 v254, 4, v254
	v_mov_b32_e32 v255, 0
	v_lshrrev_b32_e32 v245, 7, v138
	s_mov_b64 s[40:41], 0x10a50000
	s_mov_b64 s[42:43], 0x10a51000
	v_add_u32_e32 v150, v1, v0
	v_add_u32_e32 v151, v128, v2
	v_add_u32_e32 v152, v128, v3
	v_add_u32_e32 v153, v128, v4
	v_add_u32_e32 v154, v128, v5
	v_add_u32_e32 v155, v128, v6
	v_add_u32_e32 v156, v128, v7
	v_add_u32_e32 v157, v128, v8
	v_add_u32_e32 v158, v128, v9
	s_branch .LBB0_1154

.LBB0_1154:
	s_lshr_b32 s10, s88, 3
	s_mul_i32 s10, s10, s29
	s_add_i32 s10, s10, s28
	v_mov_b32_e32 v2, v181
	s_lshl_b32 s59, s10, 8
	s_lshl_b32 s10, s88, 7
	v_ashrrev_i32_e32 v163, 2, v2
	v_add_u32_e32 v0, s59, v245
	v_lshlrev_b32_e32 v3, 3, v2
	v_ashrrev_i32_e32 v1, 31, v0
	v_bitop3_b32 v4, v3, 24, v2 bitop3:0x48
	v_lshlrev_b32_e32 v165, 4, v2
	s_and_b32 s10, s10, 0x380
	v_lshlrev_b64 v[0:1], 13, v[0:1]
	s_and_b64 vcc, exec, s[46:47]
	v_add_u32_e32 v164, 0x1000, v165
	v_add_u32_e32 v162, 0x2000, v165
	v_add_u32_e32 v161, 0x3000, v165
	v_add_u32_e32 v160, 0x4000, v165
	v_add_u32_e32 v159, 0x5000, v165
	v_lshlrev_b32_e32 v132, 1, v4
	s_cbranch_vccnz .LBB0_1156
	v_lshl_add_u64 v[4:5], s[20:21], 0, v[0:1]
	v_mov_b32_e32 v133, v129
	v_readfirstlane_b32 s24, v165
	v_lshl_add_u64 v[4:5], v[4:5], 0, v[254:255]
	v_add_u32_e32 v6, s10, v163
	s_mov_b32 m0, s24
	v_readfirstlane_b32 s24, v164
	v_ashrrev_i32_e32 v7, 31, v6
	s_barrier
	global_load_lds_dwordx4 v[4:5], off
	v_lshl_add_u64 v[8:9], v[4:5], 0, s[12:13]
	s_mov_b32 m0, s24
	v_readfirstlane_b32 s24, v162
	v_lshlrev_b64 v[6:7], 6, v[6:7]
	global_load_lds_dwordx4 v[8:9], off
	v_lshl_add_u64 v[8:9], v[4:5], 0, s[14:15]
	s_mov_b32 m0, s24
	v_readfirstlane_b32 s24, v161
	v_lshl_add_u64 v[6:7], s[8:9], 0, v[6:7]
	global_load_lds_dwordx4 v[8:9], off
	v_lshl_add_u64 v[4:5], v[4:5], 0, s[16:17]
	s_mov_b32 m0, s24
	v_readfirstlane_b32 s24, v160
	v_lshl_add_u64 v[6:7], v[6:7], 0, v[132:133]
	global_load_lds_dwordx4 v[4:5], off
	s_mov_b32 m0, s24
	v_readfirstlane_b32 s24, v159
	global_load_lds_dwordx4 v[6:7], off
	v_lshl_add_u64 v[4:5], v[6:7], 0, s[30:31]
	s_mov_b32 m0, s24
	s_nop 0
	global_load_lds_dwordx4 v[4:5], off
.LBB0_1156:
	v_xor_b32_e32 v3, v3, v2
	v_lshlrev_b32_e32 v2, 6, v2
	v_and_b32_e32 v168, 0x1000, v2
	v_and_b32_e32 v166, 0x3c0, v2
	v_and_b32_e32 v167, 0xffffe000, v2
	v_lshlrev_b32_e32 v2, 1, v3
	v_and_b32_e32 v128, 48, v2
	s_and_b32 s24, s57, 0x380
	v_lshl_add_u64 v[0:1], v[0:1], 0, v[254:255]
	v_lshl_add_u64 v[134:135], s[20:21], 0, v[0:1]
	v_add_u32_e32 v0, s24, v163
	v_ashrrev_i32_e32 v1, 31, v0
	v_lshlrev_b64 v[0:1], 6, v[0:1]
	v_or_b32_e32 v0, v0, v128
	v_lshl_add_u64 v[136:137], s[20:21], 0, v[0:1]
	v_mov_b32_e32 v0, 0
	v_and_b32_e32 v133, 48, v3
	s_mov_b32 s46, 1
	s_mov_b64 s[44:45], 0
	v_mov_b32_e32 v1, v0
	v_mov_b32_e32 v2, v0
	v_mov_b32_e32 v3, v0
	v_mov_b32_e32 v4, v0
	v_mov_b32_e32 v5, v0
	v_mov_b32_e32 v6, v0
	v_mov_b32_e32 v7, v0
	v_mov_b32_e32 v8, v0
	v_mov_b32_e32 v9, v0
	v_mov_b32_e32 v10, v0
	v_mov_b32_e32 v11, v0
	v_mov_b32_e32 v12, v0
	v_mov_b32_e32 v13, v0
	v_mov_b32_e32 v14, v0
	v_mov_b32_e32 v15, v0
	v_mov_b32_e32 v16, v0
	v_mov_b32_e32 v17, v0
	v_mov_b32_e32 v18, v0
	v_mov_b32_e32 v19, v0
	v_mov_b32_e32 v20, v0
	v_mov_b32_e32 v21, v0
	v_mov_b32_e32 v22, v0
	v_mov_b32_e32 v23, v0
	v_mov_b32_e32 v24, v0
	v_mov_b32_e32 v25, v0
	v_mov_b32_e32 v26, v0
	v_mov_b32_e32 v27, v0
	v_mov_b32_e32 v28, v0
	v_mov_b32_e32 v29, v0
	v_mov_b32_e32 v30, v0
	v_mov_b32_e32 v31, v0
	v_mov_b32_e32 v32, v0
	v_mov_b32_e32 v33, v0
	v_mov_b32_e32 v34, v0
	v_mov_b32_e32 v35, v0
	v_mov_b32_e32 v36, v0
	v_mov_b32_e32 v37, v0
	v_mov_b32_e32 v38, v0
	v_mov_b32_e32 v39, v0
	v_mov_b32_e32 v40, v0
	v_mov_b32_e32 v41, v0
	v_mov_b32_e32 v42, v0
	v_mov_b32_e32 v43, v0
	v_mov_b32_e32 v44, v0
	v_mov_b32_e32 v45, v0
	v_mov_b32_e32 v46, v0
	v_mov_b32_e32 v47, v0
	v_mov_b32_e32 v48, v0
	v_mov_b32_e32 v49, v0
	v_mov_b32_e32 v50, v0
	v_mov_b32_e32 v51, v0
	v_mov_b32_e32 v52, v0
	v_mov_b32_e32 v53, v0
	v_mov_b32_e32 v54, v0
	v_mov_b32_e32 v55, v0
	v_mov_b32_e32 v56, v0
	v_mov_b32_e32 v57, v0
	v_mov_b32_e32 v58, v0
	v_mov_b32_e32 v59, v0
	v_mov_b32_e32 v60, v0
	v_mov_b32_e32 v61, v0
	v_mov_b32_e32 v62, v0
	v_mov_b32_e32 v63, v0
	v_mov_b32_e32 v64, v0
	v_mov_b32_e32 v65, v0
	v_mov_b32_e32 v66, v0
	v_mov_b32_e32 v67, v0
	v_mov_b32_e32 v68, v0
	v_mov_b32_e32 v69, v0
	v_mov_b32_e32 v70, v0
	v_mov_b32_e32 v71, v0
	v_mov_b32_e32 v72, v0
	v_mov_b32_e32 v73, v0
	v_mov_b32_e32 v74, v0
	v_mov_b32_e32 v75, v0
	v_mov_b32_e32 v76, v0
	v_mov_b32_e32 v77, v0
	v_mov_b32_e32 v78, v0
	v_mov_b32_e32 v79, v0
	v_mov_b32_e32 v80, v0
	v_mov_b32_e32 v81, v0
	v_mov_b32_e32 v82, v0
	v_mov_b32_e32 v83, v0
	v_mov_b32_e32 v84, v0
	v_mov_b32_e32 v85, v0
	v_mov_b32_e32 v86, v0
	v_mov_b32_e32 v87, v0
	v_mov_b32_e32 v88, v0
	v_mov_b32_e32 v89, v0
	v_mov_b32_e32 v90, v0
	v_mov_b32_e32 v91, v0
	v_mov_b32_e32 v92, v0
	v_mov_b32_e32 v93, v0
	v_mov_b32_e32 v94, v0
	v_mov_b32_e32 v95, v0
	v_mov_b32_e32 v96, v0
	v_mov_b32_e32 v97, v0
	v_mov_b32_e32 v98, v0
	v_mov_b32_e32 v99, v0
	v_mov_b32_e32 v100, v0
	v_mov_b32_e32 v101, v0
	v_mov_b32_e32 v102, v0
	v_mov_b32_e32 v103, v0
	v_mov_b32_e32 v104, v0
	v_mov_b32_e32 v105, v0
	v_mov_b32_e32 v106, v0
	v_mov_b32_e32 v107, v0
	v_mov_b32_e32 v108, v0
	v_mov_b32_e32 v109, v0
	v_mov_b32_e32 v110, v0
	v_mov_b32_e32 v111, v0
	v_mov_b32_e32 v112, v0
	v_mov_b32_e32 v113, v0
	v_mov_b32_e32 v114, v0
	v_mov_b32_e32 v115, v0
	v_mov_b32_e32 v116, v0
	v_mov_b32_e32 v117, v0
	v_mov_b32_e32 v118, v0
	v_mov_b32_e32 v119, v0
	v_mov_b32_e32 v120, v0
	v_mov_b32_e32 v121, v0
	v_mov_b32_e32 v122, v0
	v_mov_b32_e32 v123, v0
	v_mov_b32_e32 v124, v0
	v_mov_b32_e32 v125, v0
	v_mov_b32_e32 v126, v0
	v_mov_b32_e32 v127, v0
	v_lshl_add_u64 v[170:171], v[134:135], 0, s[100:101]
	v_lshl_add_u64 v[172:173], v[170:171], 0, s[12:13]
	v_lshl_add_u64 v[174:175], v[172:173], 0, s[12:13]
	v_lshl_add_u64 v[176:177], v[174:175], 0, s[12:13]
	v_lshl_add_u64 v[178:179], v[136:137], 0, s[40:41]
	v_lshl_add_u64 v[250:251], v[136:137], 0, s[42:43]
	v_add3_u32 v252, v167, v166, v133
	v_add3_u32 v253, v168, v166, v133
	v_readfirstlane_b32 s98, v165
	s_nop 3
	s_add_u32 s24, s98, 0x6000
	s_mov_b32 m0, s24
	s_nop 0
	global_load_lds_dwordx4 v[170:171], off
	v_lshl_add_u64 v[170:171], v[170:171], 0, s[100:101]
	s_nop 0
	s_add_u32 s25, s24, 0x1000
	s_mov_b32 m0, s25
	s_nop 0
	global_load_lds_dwordx4 v[172:173], off
	v_lshl_add_u64 v[172:173], v[172:173], 0, s[100:101]
	s_nop 0
	s_add_u32 s25, s24, 0x2000
	s_mov_b32 m0, s25
	s_nop 0
	global_load_lds_dwordx4 v[174:175], off
	v_lshl_add_u64 v[174:175], v[174:175], 0, s[100:101]
	s_nop 0
	s_add_u32 s25, s24, 0x3000
	s_mov_b32 m0, s25
	s_nop 0
	global_load_lds_dwordx4 v[176:177], off
	v_lshl_add_u64 v[176:177], v[176:177], 0, s[100:101]
	s_nop 0
	s_add_u32 s25, s24, 0x4000
	s_mov_b32 m0, s25
	s_nop 0
	global_load_lds_dwordx4 v[178:179], off
	v_lshl_add_u64 v[178:179], v[178:179], 0, s[100:101]
	s_nop 0
	s_add_u32 s25, s24, 0x5000
	s_mov_b32 m0, s25
	s_nop 0
	global_load_lds_dwordx4 v[250:251], off
	v_lshl_add_u64 v[250:251], v[250:251], 0, s[100:101]
	s_nop 0
	s_add_u32 s24, s98, 0xc000
	s_mov_b32 m0, s24
	s_nop 0
	global_load_lds_dwordx4 v[170:171], off
	v_lshl_add_u64 v[170:171], v[170:171], 0, s[100:101]
	s_nop 0
	s_add_u32 s25, s24, 0x1000
	s_mov_b32 m0, s25
	s_nop 0
	global_load_lds_dwordx4 v[172:173], off
	v_lshl_add_u64 v[172:173], v[172:173], 0, s[100:101]
	s_nop 0
	s_add_u32 s25, s24, 0x2000
	s_mov_b32 m0, s25
	s_nop 0
	global_load_lds_dwordx4 v[174:175], off
	v_lshl_add_u64 v[174:175], v[174:175], 0, s[100:101]
	s_nop 0
	s_add_u32 s25, s24, 0x3000
	s_mov_b32 m0, s25
	s_nop 0
	global_load_lds_dwordx4 v[176:177], off
	v_lshl_add_u64 v[176:177], v[176:177], 0, s[100:101]
	s_nop 0
	s_add_u32 s25, s24, 0x4000
	s_mov_b32 m0, s25
	s_nop 0
	global_load_lds_dwordx4 v[178:179], off
	v_lshl_add_u64 v[178:179], v[178:179], 0, s[100:101]
	s_nop 0
	s_add_u32 s25, s24, 0x5000
	s_mov_b32 m0, s25
	s_nop 0
	global_load_lds_dwordx4 v[250:251], off
	v_lshl_add_u64 v[250:251], v[250:251], 0, s[100:101]
	s_nop 0
	s_waitcnt vmcnt(12) lgkmcnt(0)
	s_barrier
	ds_read_b128 v[184:187], v253 offset:16384
	ds_read_b128 v[188:191], v253 offset:17408
	ds_read_b128 v[192:195], v253 offset:18432
	ds_read_b128 v[196:199], v253 offset:19456
	ds_read_b128 v[216:219], v252 offset:0
	ds_read_b128 v[220:223], v252 offset:1024
	ds_read_b128 v[224:227], v252 offset:2048
	ds_read_b128 v[228:231], v252 offset:3072
	s_mov_b32 s44, 0
	s_movk_i32 s45, 0x6000
	s_mov_b32 s46, 0xc000
	s_mov_b32 s99, 0
.Lg5_loop:
	v_add_u32_e32 v169, s44, v252
	ds_read_b128 v[232:235], v169 offset:4096
	ds_read_b128 v[236:239], v169 offset:5120
	ds_read_b128 v[240:243], v169 offset:6144
	ds_read_b128 v[246:249], v169 offset:7168
	v_add_u32_e32 v128, s45, v252
	v_add_u32_e32 v133, s45, v253
	s_waitcnt lgkmcnt(7)
	v_mfma_f32_16x16x32_bf16 v[124:127], v[184:187], v[216:219], v[124:127]
	v_mfma_f32_16x16x32_bf16 v[120:123], v[188:191], v[216:219], v[120:123]
	v_mfma_f32_16x16x32_bf16 v[116:119], v[192:195], v[216:219], v[116:119]
	v_mfma_f32_16x16x32_bf16 v[112:115], v[196:199], v[216:219], v[112:115]
	s_waitcnt lgkmcnt(6)
	v_mfma_f32_16x16x32_bf16 v[108:111], v[184:187], v[220:223], v[108:111]
	v_mfma_f32_16x16x32_bf16 v[104:107], v[188:191], v[220:223], v[104:107]
	v_mfma_f32_16x16x32_bf16 v[100:103], v[192:195], v[220:223], v[100:103]
	v_mfma_f32_16x16x32_bf16 v[96:99], v[196:199], v[220:223], v[96:99]
	s_waitcnt lgkmcnt(5)
	v_mfma_f32_16x16x32_bf16 v[92:95], v[184:187], v[224:227], v[92:95]
	v_mfma_f32_16x16x32_bf16 v[88:91], v[188:191], v[224:227], v[88:91]
	v_mfma_f32_16x16x32_bf16 v[84:87], v[192:195], v[224:227], v[84:87]
	v_mfma_f32_16x16x32_bf16 v[80:83], v[196:199], v[224:227], v[80:83]
	s_waitcnt lgkmcnt(4)
	v_mfma_f32_16x16x32_bf16 v[76:79], v[184:187], v[228:231], v[76:79]
	v_mfma_f32_16x16x32_bf16 v[72:75], v[188:191], v[228:231], v[72:75]
	v_mfma_f32_16x16x32_bf16 v[68:71], v[192:195], v[228:231], v[68:71]
	v_mfma_f32_16x16x32_bf16 v[64:67], v[196:199], v[228:231], v[64:67]
	s_waitcnt vmcnt(6) lgkmcnt(0)
	s_barrier
	v_mfma_f32_16x16x32_bf16 v[60:63], v[184:187], v[232:235], v[60:63]
	s_add_u32 s24, s44, s98
	s_mov_b32 m0, s24
	ds_read_b128 v[200:203], v133 offset:16384
	v_mfma_f32_16x16x32_bf16 v[56:59], v[188:191], v[232:235], v[56:59]
	global_load_lds_dwordx4 v[170:171], off
	v_lshl_add_u64 v[170:171], v[170:171], 0, s[100:101]
	ds_read_b128 v[204:207], v133 offset:17408
	v_mfma_f32_16x16x32_bf16 v[52:55], v[192:195], v[232:235], v[52:55]
	s_add_u32 s25, s24, 0x1000
	s_mov_b32 m0, s25
	ds_read_b128 v[208:211], v133 offset:18432
	v_mfma_f32_16x16x32_bf16 v[48:51], v[196:199], v[232:235], v[48:51]
	global_load_lds_dwordx4 v[172:173], off
	v_lshl_add_u64 v[172:173], v[172:173], 0, s[100:101]
	ds_read_b128 v[212:215], v133 offset:19456
	v_mfma_f32_16x16x32_bf16 v[44:47], v[184:187], v[236:239], v[44:47]
	s_add_u32 s25, s24, 0x2000
	s_mov_b32 m0, s25
	ds_read_b128 v[216:219], v128 offset:0
	v_mfma_f32_16x16x32_bf16 v[40:43], v[188:191], v[236:239], v[40:43]
	global_load_lds_dwordx4 v[174:175], off
	v_lshl_add_u64 v[174:175], v[174:175], 0, s[100:101]
	ds_read_b128 v[220:223], v128 offset:1024
	v_mfma_f32_16x16x32_bf16 v[36:39], v[192:195], v[236:239], v[36:39]
	s_add_u32 s25, s24, 0x3000
	s_mov_b32 m0, s25
	ds_read_b128 v[224:227], v128 offset:2048
	v_mfma_f32_16x16x32_bf16 v[32:35], v[196:199], v[236:239], v[32:35]
	global_load_lds_dwordx4 v[176:177], off
	v_lshl_add_u64 v[176:177], v[176:177], 0, s[100:101]
	ds_read_b128 v[228:231], v128 offset:3072
	v_mfma_f32_16x16x32_bf16 v[28:31], v[184:187], v[240:243], v[28:31]
	s_add_u32 s25, s24, 0x4000
	s_mov_b32 m0, s25
	v_mfma_f32_16x16x32_bf16 v[24:27], v[188:191], v[240:243], v[24:27]
	global_load_lds_dwordx4 v[178:179], off
	v_lshl_add_u64 v[178:179], v[178:179], 0, s[100:101]
	v_mfma_f32_16x16x32_bf16 v[20:23], v[192:195], v[240:243], v[20:23]
	s_add_u32 s25, s24, 0x5000
	s_mov_b32 m0, s25
	v_mfma_f32_16x16x32_bf16 v[16:19], v[196:199], v[240:243], v[16:19]
	global_load_lds_dwordx4 v[250:251], off
	v_lshl_add_u64 v[250:251], v[250:251], 0, s[100:101]
	v_mfma_f32_16x16x32_bf16 v[12:15], v[184:187], v[246:249], v[12:15]
	v_mfma_f32_16x16x32_bf16 v[8:11], v[188:191], v[246:249], v[8:11]
	v_mfma_f32_16x16x32_bf16 v[4:7], v[192:195], v[246:249], v[4:7]
	v_mfma_f32_16x16x32_bf16 v[0:3], v[196:199], v[246:249], v[0:3]
	s_mov_b32 s24, s44
	s_mov_b32 s44, s45
	s_mov_b32 s45, s46
	s_mov_b32 s46, s24
	v_add_u32_e32 v169, s44, v252
	ds_read_b128 v[232:235], v169 offset:4096
	ds_read_b128 v[236:239], v169 offset:5120
	ds_read_b128 v[240:243], v169 offset:6144
	ds_read_b128 v[246:249], v169 offset:7168
	v_add_u32_e32 v128, s45, v252
	v_add_u32_e32 v133, s45, v253
	s_waitcnt lgkmcnt(7)
	v_mfma_f32_16x16x32_bf16 v[124:127], v[200:203], v[216:219], v[124:127]
	v_mfma_f32_16x16x32_bf16 v[120:123], v[204:207], v[216:219], v[120:123]
	v_mfma_f32_16x16x32_bf16 v[116:119], v[208:211], v[216:219], v[116:119]
	v_mfma_f32_16x16x32_bf16 v[112:115], v[212:215], v[216:219], v[112:115]
	s_waitcnt lgkmcnt(6)
	v_mfma_f32_16x16x32_bf16 v[108:111], v[200:203], v[220:223], v[108:111]
	v_mfma_f32_16x16x32_bf16 v[104:107], v[204:207], v[220:223], v[104:107]
	v_mfma_f32_16x16x32_bf16 v[100:103], v[208:211], v[220:223], v[100:103]
	v_mfma_f32_16x16x32_bf16 v[96:99], v[212:215], v[220:223], v[96:99]
	s_waitcnt lgkmcnt(5)
	v_mfma_f32_16x16x32_bf16 v[92:95], v[200:203], v[224:227], v[92:95]
	v_mfma_f32_16x16x32_bf16 v[88:91], v[204:207], v[224:227], v[88:91]
	v_mfma_f32_16x16x32_bf16 v[84:87], v[208:211], v[224:227], v[84:87]
	v_mfma_f32_16x16x32_bf16 v[80:83], v[212:215], v[224:227], v[80:83]
	s_waitcnt lgkmcnt(4)
	v_mfma_f32_16x16x32_bf16 v[76:79], v[200:203], v[228:231], v[76:79]
	v_mfma_f32_16x16x32_bf16 v[72:75], v[204:207], v[228:231], v[72:75]
	v_mfma_f32_16x16x32_bf16 v[68:71], v[208:211], v[228:231], v[68:71]
	v_mfma_f32_16x16x32_bf16 v[64:67], v[212:215], v[228:231], v[64:67]
	s_waitcnt vmcnt(6) lgkmcnt(0)
	s_barrier
	v_mfma_f32_16x16x32_bf16 v[60:63], v[200:203], v[232:235], v[60:63]
	s_add_u32 s24, s44, s98
	s_mov_b32 m0, s24
	ds_read_b128 v[184:187], v133 offset:16384
	v_mfma_f32_16x16x32_bf16 v[56:59], v[204:207], v[232:235], v[56:59]
	global_load_lds_dwordx4 v[170:171], off
	v_lshl_add_u64 v[170:171], v[170:171], 0, s[100:101]
	ds_read_b128 v[188:191], v133 offset:17408
	v_mfma_f32_16x16x32_bf16 v[52:55], v[208:211], v[232:235], v[52:55]
	s_add_u32 s25, s24, 0x1000
	s_mov_b32 m0, s25
	ds_read_b128 v[192:195], v133 offset:18432
	v_mfma_f32_16x16x32_bf16 v[48:51], v[212:215], v[232:235], v[48:51]
	global_load_lds_dwordx4 v[172:173], off
	v_lshl_add_u64 v[172:173], v[172:173], 0, s[100:101]
	ds_read_b128 v[196:199], v133 offset:19456
	v_mfma_f32_16x16x32_bf16 v[44:47], v[200:203], v[236:239], v[44:47]
	s_add_u32 s25, s24, 0x2000
	s_mov_b32 m0, s25
	ds_read_b128 v[216:219], v128 offset:0
	v_mfma_f32_16x16x32_bf16 v[40:43], v[204:207], v[236:239], v[40:43]
	global_load_lds_dwordx4 v[174:175], off
	v_lshl_add_u64 v[174:175], v[174:175], 0, s[100:101]
	ds_read_b128 v[220:223], v128 offset:1024
	v_mfma_f32_16x16x32_bf16 v[36:39], v[208:211], v[236:239], v[36:39]
	s_add_u32 s25, s24, 0x3000
	s_mov_b32 m0, s25
	ds_read_b128 v[224:227], v128 offset:2048
	v_mfma_f32_16x16x32_bf16 v[32:35], v[212:215], v[236:239], v[32:35]
	global_load_lds_dwordx4 v[176:177], off
	v_lshl_add_u64 v[176:177], v[176:177], 0, s[100:101]
	ds_read_b128 v[228:231], v128 offset:3072
	v_mfma_f32_16x16x32_bf16 v[28:31], v[200:203], v[240:243], v[28:31]
	s_add_u32 s25, s24, 0x4000
	s_mov_b32 m0, s25
	v_mfma_f32_16x16x32_bf16 v[24:27], v[204:207], v[240:243], v[24:27]
	global_load_lds_dwordx4 v[178:179], off
	v_lshl_add_u64 v[178:179], v[178:179], 0, s[100:101]
	v_mfma_f32_16x16x32_bf16 v[20:23], v[208:211], v[240:243], v[20:23]
	s_add_u32 s25, s24, 0x5000
	s_mov_b32 m0, s25
	v_mfma_f32_16x16x32_bf16 v[16:19], v[212:215], v[240:243], v[16:19]
	global_load_lds_dwordx4 v[250:251], off
	v_lshl_add_u64 v[250:251], v[250:251], 0, s[100:101]
	v_mfma_f32_16x16x32_bf16 v[12:15], v[200:203], v[246:249], v[12:15]
	v_mfma_f32_16x16x32_bf16 v[8:11], v[204:207], v[246:249], v[8:11]
	v_mfma_f32_16x16x32_bf16 v[4:7], v[208:211], v[246:249], v[4:7]
	v_mfma_f32_16x16x32_bf16 v[0:3], v[212:215], v[246:249], v[0:3]
	s_mov_b32 s24, s44
	s_mov_b32 s44, s45
	s_mov_b32 s45, s46
	s_mov_b32 s46, s24
	s_add_i32 s99, s99, 1
	s_cmp_lt_u32 s99, 14
	s_cbranch_scc1 .Lg5_loop
	v_add_u32_e32 v169, s44, v252
	ds_read_b128 v[232:235], v169 offset:4096
	ds_read_b128 v[236:239], v169 offset:5120
	ds_read_b128 v[240:243], v169 offset:6144
	ds_read_b128 v[246:249], v169 offset:7168
	v_add_u32_e32 v128, s45, v252
	v_add_u32_e32 v133, s45, v253
	s_waitcnt lgkmcnt(7)
	v_mfma_f32_16x16x32_bf16 v[124:127], v[184:187], v[216:219], v[124:127]
	v_mfma_f32_16x16x32_bf16 v[120:123], v[188:191], v[216:219], v[120:123]
	v_mfma_f32_16x16x32_bf16 v[116:119], v[192:195], v[216:219], v[116:119]
	v_mfma_f32_16x16x32_bf16 v[112:115], v[196:199], v[216:219], v[112:115]
	s_waitcnt lgkmcnt(6)
	v_mfma_f32_16x16x32_bf16 v[108:111], v[184:187], v[220:223], v[108:111]
	v_mfma_f32_16x16x32_bf16 v[104:107], v[188:191], v[220:223], v[104:107]
	v_mfma_f32_16x16x32_bf16 v[100:103], v[192:195], v[220:223], v[100:103]
	v_mfma_f32_16x16x32_bf16 v[96:99], v[196:199], v[220:223], v[96:99]
	s_waitcnt lgkmcnt(5)
	v_mfma_f32_16x16x32_bf16 v[92:95], v[184:187], v[224:227], v[92:95]
	v_mfma_f32_16x16x32_bf16 v[88:91], v[188:191], v[224:227], v[88:91]
	v_mfma_f32_16x16x32_bf16 v[84:87], v[192:195], v[224:227], v[84:87]
	v_mfma_f32_16x16x32_bf16 v[80:83], v[196:199], v[224:227], v[80:83]
	s_waitcnt lgkmcnt(4)
	v_mfma_f32_16x16x32_bf16 v[76:79], v[184:187], v[228:231], v[76:79]
	v_mfma_f32_16x16x32_bf16 v[72:75], v[188:191], v[228:231], v[72:75]
	v_mfma_f32_16x16x32_bf16 v[68:71], v[192:195], v[228:231], v[68:71]
	v_mfma_f32_16x16x32_bf16 v[64:67], v[196:199], v[228:231], v[64:67]
	s_waitcnt vmcnt(6) lgkmcnt(0)
	s_barrier
	v_mfma_f32_16x16x32_bf16 v[60:63], v[184:187], v[232:235], v[60:63]
	s_add_u32 s24, s44, s98
	s_mov_b32 m0, s24
	ds_read_b128 v[200:203], v133 offset:16384
	v_mfma_f32_16x16x32_bf16 v[56:59], v[188:191], v[232:235], v[56:59]
	global_load_lds_dwordx4 v[170:171], off
	v_lshl_add_u64 v[170:171], v[170:171], 0, s[100:101]
	ds_read_b128 v[204:207], v133 offset:17408
	v_mfma_f32_16x16x32_bf16 v[52:55], v[192:195], v[232:235], v[52:55]
	s_add_u32 s25, s24, 0x1000
	s_mov_b32 m0, s25
	ds_read_b128 v[208:211], v133 offset:18432
	v_mfma_f32_16x16x32_bf16 v[48:51], v[196:199], v[232:235], v[48:51]
	global_load_lds_dwordx4 v[172:173], off
	v_lshl_add_u64 v[172:173], v[172:173], 0, s[100:101]
	ds_read_b128 v[212:215], v133 offset:19456
	v_mfma_f32_16x16x32_bf16 v[44:47], v[184:187], v[236:239], v[44:47]
	s_add_u32 s25, s24, 0x2000
	s_mov_b32 m0, s25
	ds_read_b128 v[216:219], v128 offset:0
	v_mfma_f32_16x16x32_bf16 v[40:43], v[188:191], v[236:239], v[40:43]
	global_load_lds_dwordx4 v[174:175], off
	v_lshl_add_u64 v[174:175], v[174:175], 0, s[100:101]
	ds_read_b128 v[220:223], v128 offset:1024
	v_mfma_f32_16x16x32_bf16 v[36:39], v[192:195], v[236:239], v[36:39]
	s_add_u32 s25, s24, 0x3000
	s_mov_b32 m0, s25
	ds_read_b128 v[224:227], v128 offset:2048
	v_mfma_f32_16x16x32_bf16 v[32:35], v[196:199], v[236:239], v[32:35]
	global_load_lds_dwordx4 v[176:177], off
	v_lshl_add_u64 v[176:177], v[176:177], 0, s[100:101]
	ds_read_b128 v[228:231], v128 offset:3072
	v_mfma_f32_16x16x32_bf16 v[28:31], v[184:187], v[240:243], v[28:31]
	s_add_u32 s25, s24, 0x4000
	s_mov_b32 m0, s25
	v_mfma_f32_16x16x32_bf16 v[24:27], v[188:191], v[240:243], v[24:27]
	global_load_lds_dwordx4 v[178:179], off
	v_lshl_add_u64 v[178:179], v[178:179], 0, s[100:101]
	v_mfma_f32_16x16x32_bf16 v[20:23], v[192:195], v[240:243], v[20:23]
	s_add_u32 s25, s24, 0x5000
	s_mov_b32 m0, s25
	v_mfma_f32_16x16x32_bf16 v[16:19], v[196:199], v[240:243], v[16:19]
	global_load_lds_dwordx4 v[250:251], off
	v_lshl_add_u64 v[250:251], v[250:251], 0, s[100:101]
	v_mfma_f32_16x16x32_bf16 v[12:15], v[184:187], v[246:249], v[12:15]
	v_mfma_f32_16x16x32_bf16 v[8:11], v[188:191], v[246:249], v[8:11]
	v_mfma_f32_16x16x32_bf16 v[4:7], v[192:195], v[246:249], v[4:7]
	v_mfma_f32_16x16x32_bf16 v[0:3], v[196:199], v[246:249], v[0:3]
	s_mov_b32 s24, s44
	s_mov_b32 s44, s45
	s_mov_b32 s45, s46
	s_mov_b32 s46, s24
	v_add_u32_e32 v169, s44, v252
	ds_read_b128 v[232:235], v169 offset:4096
	ds_read_b128 v[236:239], v169 offset:5120
	ds_read_b128 v[240:243], v169 offset:6144
	ds_read_b128 v[246:249], v169 offset:7168
	v_add_u32_e32 v128, s45, v252
	v_add_u32_e32 v133, s45, v253
	s_waitcnt lgkmcnt(7)
	v_mfma_f32_16x16x32_bf16 v[124:127], v[200:203], v[216:219], v[124:127]
	v_mfma_f32_16x16x32_bf16 v[120:123], v[204:207], v[216:219], v[120:123]
	v_mfma_f32_16x16x32_bf16 v[116:119], v[208:211], v[216:219], v[116:119]
	v_mfma_f32_16x16x32_bf16 v[112:115], v[212:215], v[216:219], v[112:115]
	s_waitcnt lgkmcnt(6)
	v_mfma_f32_16x16x32_bf16 v[108:111], v[200:203], v[220:223], v[108:111]
	v_mfma_f32_16x16x32_bf16 v[104:107], v[204:207], v[220:223], v[104:107]
	v_mfma_f32_16x16x32_bf16 v[100:103], v[208:211], v[220:223], v[100:103]
	v_mfma_f32_16x16x32_bf16 v[96:99], v[212:215], v[220:223], v[96:99]
	s_waitcnt lgkmcnt(5)
	v_mfma_f32_16x16x32_bf16 v[92:95], v[200:203], v[224:227], v[92:95]
	v_mfma_f32_16x16x32_bf16 v[88:91], v[204:207], v[224:227], v[88:91]
	v_mfma_f32_16x16x32_bf16 v[84:87], v[208:211], v[224:227], v[84:87]
	v_mfma_f32_16x16x32_bf16 v[80:83], v[212:215], v[224:227], v[80:83]
	s_waitcnt lgkmcnt(4)
	v_mfma_f32_16x16x32_bf16 v[76:79], v[200:203], v[228:231], v[76:79]
	v_mfma_f32_16x16x32_bf16 v[72:75], v[204:207], v[228:231], v[72:75]
	v_mfma_f32_16x16x32_bf16 v[68:71], v[208:211], v[228:231], v[68:71]
	v_mfma_f32_16x16x32_bf16 v[64:67], v[212:215], v[228:231], v[64:67]
	s_waitcnt vmcnt(6) lgkmcnt(0)
	s_barrier
	v_mfma_f32_16x16x32_bf16 v[60:63], v[200:203], v[232:235], v[60:63]
	ds_read_b128 v[184:187], v133 offset:16384
	v_mfma_f32_16x16x32_bf16 v[56:59], v[204:207], v[232:235], v[56:59]
	ds_read_b128 v[188:191], v133 offset:17408
	v_mfma_f32_16x16x32_bf16 v[52:55], v[208:211], v[232:235], v[52:55]
	ds_read_b128 v[192:195], v133 offset:18432
	v_mfma_f32_16x16x32_bf16 v[48:51], v[212:215], v[232:235], v[48:51]
	ds_read_b128 v[196:199], v133 offset:19456
	v_mfma_f32_16x16x32_bf16 v[44:47], v[200:203], v[236:239], v[44:47]
	ds_read_b128 v[216:219], v128 offset:0
	v_mfma_f32_16x16x32_bf16 v[40:43], v[204:207], v[236:239], v[40:43]
	ds_read_b128 v[220:223], v128 offset:1024
	v_mfma_f32_16x16x32_bf16 v[36:39], v[208:211], v[236:239], v[36:39]
	ds_read_b128 v[224:227], v128 offset:2048
	v_mfma_f32_16x16x32_bf16 v[32:35], v[212:215], v[236:239], v[32:35]
	ds_read_b128 v[228:231], v128 offset:3072
	v_mfma_f32_16x16x32_bf16 v[28:31], v[200:203], v[240:243], v[28:31]
	v_mfma_f32_16x16x32_bf16 v[24:27], v[204:207], v[240:243], v[24:27]
	v_mfma_f32_16x16x32_bf16 v[20:23], v[208:211], v[240:243], v[20:23]
	v_mfma_f32_16x16x32_bf16 v[16:19], v[212:215], v[240:243], v[16:19]
	v_mfma_f32_16x16x32_bf16 v[12:15], v[200:203], v[246:249], v[12:15]
	v_mfma_f32_16x16x32_bf16 v[8:11], v[204:207], v[246:249], v[8:11]
	v_mfma_f32_16x16x32_bf16 v[4:7], v[208:211], v[246:249], v[4:7]
	v_mfma_f32_16x16x32_bf16 v[0:3], v[212:215], v[246:249], v[0:3]
	s_mov_b32 s24, s44
	s_mov_b32 s44, s45
	s_mov_b32 s45, s46
	s_mov_b32 s46, s24
	v_add_u32_e32 v169, s44, v252
	ds_read_b128 v[232:235], v169 offset:4096
	ds_read_b128 v[236:239], v169 offset:5120
	ds_read_b128 v[240:243], v169 offset:6144
	ds_read_b128 v[246:249], v169 offset:7168
	v_add_u32_e32 v128, s45, v252
	v_add_u32_e32 v133, s45, v253
	s_waitcnt lgkmcnt(7)
	v_mfma_f32_16x16x32_bf16 v[124:127], v[184:187], v[216:219], v[124:127]
	v_mfma_f32_16x16x32_bf16 v[120:123], v[188:191], v[216:219], v[120:123]
	v_mfma_f32_16x16x32_bf16 v[116:119], v[192:195], v[216:219], v[116:119]
	v_mfma_f32_16x16x32_bf16 v[112:115], v[196:199], v[216:219], v[112:115]
	s_waitcnt lgkmcnt(6)
	v_mfma_f32_16x16x32_bf16 v[108:111], v[184:187], v[220:223], v[108:111]
	v_mfma_f32_16x16x32_bf16 v[104:107], v[188:191], v[220:223], v[104:107]
	v_mfma_f32_16x16x32_bf16 v[100:103], v[192:195], v[220:223], v[100:103]
	v_mfma_f32_16x16x32_bf16 v[96:99], v[196:199], v[220:223], v[96:99]
	s_waitcnt lgkmcnt(5)
	v_mfma_f32_16x16x32_bf16 v[92:95], v[184:187], v[224:227], v[92:95]
	v_mfma_f32_16x16x32_bf16 v[88:91], v[188:191], v[224:227], v[88:91]
	v_mfma_f32_16x16x32_bf16 v[84:87], v[192:195], v[224:227], v[84:87]
	v_mfma_f32_16x16x32_bf16 v[80:83], v[196:199], v[224:227], v[80:83]
	s_waitcnt lgkmcnt(4)
	v_mfma_f32_16x16x32_bf16 v[76:79], v[184:187], v[228:231], v[76:79]
	v_mfma_f32_16x16x32_bf16 v[72:75], v[188:191], v[228:231], v[72:75]
	v_mfma_f32_16x16x32_bf16 v[68:71], v[192:195], v[228:231], v[68:71]
	v_mfma_f32_16x16x32_bf16 v[64:67], v[196:199], v[228:231], v[64:67]
	s_waitcnt vmcnt(0) lgkmcnt(0)
	s_barrier
	v_mfma_f32_16x16x32_bf16 v[60:63], v[184:187], v[232:235], v[60:63]
	ds_read_b128 v[200:203], v133 offset:16384
	v_mfma_f32_16x16x32_bf16 v[56:59], v[188:191], v[232:235], v[56:59]
	ds_read_b128 v[204:207], v133 offset:17408
	v_mfma_f32_16x16x32_bf16 v[52:55], v[192:195], v[232:235], v[52:55]
	ds_read_b128 v[208:211], v133 offset:18432
	v_mfma_f32_16x16x32_bf16 v[48:51], v[196:199], v[232:235], v[48:51]
	ds_read_b128 v[212:215], v133 offset:19456
	v_mfma_f32_16x16x32_bf16 v[44:47], v[184:187], v[236:239], v[44:47]
	ds_read_b128 v[216:219], v128 offset:0
	v_mfma_f32_16x16x32_bf16 v[40:43], v[188:191], v[236:239], v[40:43]
	ds_read_b128 v[220:223], v128 offset:1024
	v_mfma_f32_16x16x32_bf16 v[36:39], v[192:195], v[236:239], v[36:39]
	ds_read_b128 v[224:227], v128 offset:2048
	v_mfma_f32_16x16x32_bf16 v[32:35], v[196:199], v[236:239], v[32:35]
	ds_read_b128 v[228:231], v128 offset:3072
	v_mfma_f32_16x16x32_bf16 v[28:31], v[184:187], v[240:243], v[28:31]
	v_mfma_f32_16x16x32_bf16 v[24:27], v[188:191], v[240:243], v[24:27]
	v_mfma_f32_16x16x32_bf16 v[20:23], v[192:195], v[240:243], v[20:23]
	v_mfma_f32_16x16x32_bf16 v[16:19], v[196:199], v[240:243], v[16:19]
	v_mfma_f32_16x16x32_bf16 v[12:15], v[184:187], v[246:249], v[12:15]
	v_mfma_f32_16x16x32_bf16 v[8:11], v[188:191], v[246:249], v[8:11]
	v_mfma_f32_16x16x32_bf16 v[4:7], v[192:195], v[246:249], v[4:7]
	v_mfma_f32_16x16x32_bf16 v[0:3], v[196:199], v[246:249], v[0:3]
	s_mov_b32 s24, s44
	s_mov_b32 s44, s45
	s_mov_b32 s45, s46
	s_mov_b32 s46, s24
	v_add_u32_e32 v169, s44, v252
	ds_read_b128 v[232:235], v169 offset:4096
	ds_read_b128 v[236:239], v169 offset:5120
	ds_read_b128 v[240:243], v169 offset:6144
	ds_read_b128 v[246:249], v169 offset:7168
	s_waitcnt lgkmcnt(7)
	v_mfma_f32_16x16x32_bf16 v[124:127], v[200:203], v[216:219], v[124:127]
	v_mfma_f32_16x16x32_bf16 v[120:123], v[204:207], v[216:219], v[120:123]
	v_mfma_f32_16x16x32_bf16 v[116:119], v[208:211], v[216:219], v[116:119]
	v_mfma_f32_16x16x32_bf16 v[112:115], v[212:215], v[216:219], v[112:115]
	s_waitcnt lgkmcnt(6)
	v_mfma_f32_16x16x32_bf16 v[108:111], v[200:203], v[220:223], v[108:111]
	v_mfma_f32_16x16x32_bf16 v[104:107], v[204:207], v[220:223], v[104:107]
	v_mfma_f32_16x16x32_bf16 v[100:103], v[208:211], v[220:223], v[100:103]
	v_mfma_f32_16x16x32_bf16 v[96:99], v[212:215], v[220:223], v[96:99]
	s_waitcnt lgkmcnt(5)
	v_mfma_f32_16x16x32_bf16 v[92:95], v[200:203], v[224:227], v[92:95]
	v_mfma_f32_16x16x32_bf16 v[88:91], v[204:207], v[224:227], v[88:91]
	v_mfma_f32_16x16x32_bf16 v[84:87], v[208:211], v[224:227], v[84:87]
	v_mfma_f32_16x16x32_bf16 v[80:83], v[212:215], v[224:227], v[80:83]
	s_waitcnt lgkmcnt(4)
	v_mfma_f32_16x16x32_bf16 v[76:79], v[200:203], v[228:231], v[76:79]
	v_mfma_f32_16x16x32_bf16 v[72:75], v[204:207], v[228:231], v[72:75]
	v_mfma_f32_16x16x32_bf16 v[68:71], v[208:211], v[228:231], v[68:71]
	v_mfma_f32_16x16x32_bf16 v[64:67], v[212:215], v[228:231], v[64:67]
	s_waitcnt lgkmcnt(0)
	s_barrier
	v_mfma_f32_16x16x32_bf16 v[60:63], v[200:203], v[232:235], v[60:63]
	v_mfma_f32_16x16x32_bf16 v[56:59], v[204:207], v[232:235], v[56:59]
	v_mfma_f32_16x16x32_bf16 v[52:55], v[208:211], v[232:235], v[52:55]
	v_mfma_f32_16x16x32_bf16 v[48:51], v[212:215], v[232:235], v[48:51]
	v_mfma_f32_16x16x32_bf16 v[44:47], v[200:203], v[236:239], v[44:47]
	v_mfma_f32_16x16x32_bf16 v[40:43], v[204:207], v[236:239], v[40:43]
	v_mfma_f32_16x16x32_bf16 v[36:39], v[208:211], v[236:239], v[36:39]
	v_mfma_f32_16x16x32_bf16 v[32:35], v[212:215], v[236:239], v[32:35]
	v_mfma_f32_16x16x32_bf16 v[28:31], v[200:203], v[240:243], v[28:31]
	v_mfma_f32_16x16x32_bf16 v[24:27], v[204:207], v[240:243], v[24:27]
	v_mfma_f32_16x16x32_bf16 v[20:23], v[208:211], v[240:243], v[20:23]
	v_mfma_f32_16x16x32_bf16 v[16:19], v[212:215], v[240:243], v[16:19]
	v_mfma_f32_16x16x32_bf16 v[12:15], v[200:203], v[246:249], v[12:15]
	v_mfma_f32_16x16x32_bf16 v[8:11], v[204:207], v[246:249], v[8:11]
	v_mfma_f32_16x16x32_bf16 v[4:7], v[208:211], v[246:249], v[4:7]
	v_mfma_f32_16x16x32_bf16 v[0:3], v[212:215], v[246:249], v[0:3]
	s_mov_b32 s24, s44
	s_mov_b32 s44, s45
	s_mov_b32 s45, s46
	s_mov_b32 s46, s24
	s_add_i32 s88, s88, s89
	s_cmp_ge_i32 s88, s56
	s_cselect_b64 s[44:45], -1, 0
	s_cmp_lt_i32 s88, s56
	s_cbranch_scc0 .LBB0_1160
	s_lshr_b32 s24, s88, 3
	s_mul_i32 s24, s24, s29
	s_add_i32 s24, s24, s28
	s_lshl_b32 s25, s88, 7
	s_and_b32 s25, s25, 0x380
	v_lshl_add_u32 v134, s24, 8, v245
	v_ashrrev_i32_e32 v135, 31, v134
	v_add_u32_e32 v136, s25, v163
	v_lshlrev_b64 v[134:135], 13, v[134:135]
	v_ashrrev_i32_e32 v137, 31, v136
	v_lshl_add_u64 v[134:135], s[20:21], 0, v[134:135]
	v_mov_b32_e32 v133, v129
	v_lshlrev_b64 v[136:137], 6, v[136:137]
	v_readfirstlane_b32 s24, v165
	v_lshl_add_u64 v[134:135], v[134:135], 0, v[254:255]
	v_lshl_add_u64 v[136:137], s[8:9], 0, v[136:137]
	s_mov_b32 m0, s24
	v_readfirstlane_b32 s24, v164
	v_lshl_add_u64 v[132:133], v[136:137], 0, v[132:133]
	global_load_lds_dwordx4 v[134:135], off
	v_lshl_add_u64 v[136:137], v[134:135], 0, s[12:13]
	s_mov_b32 m0, s24
	v_readfirstlane_b32 s24, v162
	global_load_lds_dwordx4 v[136:137], off
	v_lshl_add_u64 v[136:137], v[134:135], 0, s[14:15]
	s_mov_b32 m0, s24
	v_readfirstlane_b32 s24, v161
	global_load_lds_dwordx4 v[136:137], off
	v_lshl_add_u64 v[134:135], v[134:135], 0, s[16:17]
	s_mov_b32 m0, s24
	v_readfirstlane_b32 s24, v160
	global_load_lds_dwordx4 v[134:135], off
	s_mov_b32 m0, s24
	v_readfirstlane_b32 s24, v159
	global_load_lds_dwordx4 v[132:133], off
	v_lshl_add_u64 v[132:133], v[132:133], 0, s[30:31]
	s_mov_b32 m0, s24
	s_nop 0
	global_load_lds_dwordx4 v[132:133], off
